# v18 + prefetched (batched) loads in m2 phase: S5 pass-A B-fragments and pool_item inputs/weights
# baseline (speedup 1.0000x reference)
; #define TIDX tid_()
; DEVI unsigned pk_bf16(float lo, float hi) { const bf16x2n r = __builtin_convertvector((f32x2v){lo, hi}, bf16x2n); return __builtin_bit_cast(unsigned, r); }
; DEVI void s5_bfrags(const Params& p, int l, int G, bf16x8 (&bf)[8]) {
;     const int lane = TIDX & 63, l16 = lane & 15, quad = lane >> 4;
;     const float* S5B = (const float*)(p.ws + OFF_S5B);
; #pragma unroll
;     for (int nt = 0; nt < 8; ++nt) {
;         const int n = nt * 16 + l16, pp = n & 63, im = n >> 6;
;         const float* src = S5B + ((size_t)(l * 16 + G) * 64 + pp) * 32 + im * 16 + (quad & 1) * 8;
;         const f32x4 a = *(const f32x4*)src, c = *(const f32x4*)(src + 4);
;         u32x4 v = (u32x4){pk_bf16(a[0], a[1]), pk_bf16(a[2], a[3]), pk_bf16(c[0], c[1]), pk_bf16(c[2], c[3])};
;         if (quad >= 2) v = (u32x4){0u, 0u, 0u, 0u};
;         bf[nt] = __builtin_bit_cast(bf16x8, v);
;     }
; DEVI void s5_pass_a(const Params& p, int l, int witem, float* wl) {
;     unsigned char* ws = p.ws;
;     const int lane = TIDX & 63;
;     const int G = witem & 15, k = (witem >> 4) & 127, b = witem >> 11;
;     const int sidx = (l * 16 + G) * 64 + lane;
;     const float4 a4 = ((const float4*)(ws + OFF_S5A))[sidx];
;     bf16x8 bfr[8];
;     s5_bfrags(p, l, G, bfr);
;     float* us = wl;
;     s5_load_u((const float*)(ws + OFF_USSM), b * S_ + k * 64, G, us, lane);
.LBB0_45:
	s_cmpk_gt_i32 s64, 0x7f
	s_mov_b64 s[0:1], -1
	s_barrier
	s_cbranch_scc0 .LBB0_69
	s_cmpk_gt_u32 s64, 0x47f
	s_cbranch_scc0 .LBB0_52
	v_mov_b32_e32 v0, v133
	s_lshl_b32 s1, s64, 2
	v_readfirstlane_b32 s0, v0
	s_ashr_i32 s0, s0, 6
	s_add_i32 s1, s1, s0
	s_addk_i32 s1, 0xee00
	s_lshl_b32 s38, s0, 14
	s_and_b32 s0, s1, 15
	v_mov_b32_e32 v0, v133
	s_lshl_b32 s22, s0, 6
	s_bfe_u32 s30, s1, 0x70004
	v_and_b32_e32 v40, 63, v0
	s_ashr_i32 s31, s1, 11
	s_or_b32 s1, s22, s4
	v_or_b32_e32 v2, s1, v40
	v_ashrrev_i32_e32 v3, 31, v2
	s_or_b32 s0, s0, s6
	v_lshl_add_u64 v[2:3], v[2:3], 4, s[14:15]
	v_mov_b32_e32 v4, v133
	s_ashr_i32 s1, s0, 31
	global_load_dwordx2 v[34:35], v[2:3], off
	s_lshl_b64 s[0:1], s[0:1], 13
	v_and_b32_e32 v0, 32, v4
	s_add_u32 s0, s11, s0
	v_cmp_eq_u32_e32 vcc, 0, v0
	v_lshlrev_b32_e32 v0, 7, v4
	s_addc_u32 s1, s13, s1
	v_and_b32_e32 v0, 0x780, v0
	v_lshl_add_u64 v[2:3], s[0:1], 0, v[0:1]
	v_lshlrev_b32_e32 v0, 1, v4
	v_and_b32_e32 v0, 32, v0
	v_lshl_add_u64 v[30:31], v[2:3], 0, v[0:1]
	s_mov_b64 s[0:1], 0x1000
	v_lshl_add_u64 v[98:99], v[30:31], 0, s[0:1]
	global_load_dwordx4 v[100:103], v[30:31], off offset:16
	global_load_dwordx4 v[104:107], v[30:31], off
	global_load_dwordx4 v[108:111], v[30:31], off offset:2064
	global_load_dwordx4 v[112:115], v[30:31], off offset:2048
	global_load_dwordx4 v[116:119], v[98:99], off
	global_load_dwordx4 v[120:123], v[98:99], off offset:16
	global_load_dwordx4 v[124:127], v[98:99], off offset:2048
	global_load_dwordx4 v[128:131], v[98:99], off offset:2064
	global_load_dwordx4 v[160:163], v[30:31], off offset:80
	global_load_dwordx4 v[164:167], v[30:31], off offset:64
	global_load_dwordx4 v[168:171], v[30:31], off offset:2128
	global_load_dwordx4 v[172:175], v[30:31], off offset:2112
	global_load_dwordx4 v[176:179], v[98:99], off offset:64
	global_load_dwordx4 v[180:183], v[98:99], off offset:80
	global_load_dwordx4 v[184:187], v[98:99], off offset:2112
	global_load_dwordx4 v[188:191], v[98:99], off offset:2128
	s_mov_b64 s[0:1], 0x1000
	s_movk_i32 s39, 0x1000
	v_lshl_add_u64 v[14:15], v[30:31], 0, s[0:1]
	v_add_co_u32_e64 v32, s[0:1], s39, v30
	s_waitcnt vmcnt(15)
	v_mov_b32_e32 v2, v100
	v_mov_b32_e32 v3, v101
	v_mov_b32_e32 v4, v102
	v_mov_b32_e32 v5, v103
	v_cvt_pk_bf16_f32 v2, v2, v3
	s_waitcnt vmcnt(14)
	v_mov_b32_e32 v6, v104
	v_mov_b32_e32 v7, v105
	v_mov_b32_e32 v8, v106
	v_mov_b32_e32 v9, v107
	v_cvt_pk_bf16_f32 v0, v6, v7
	v_cvt_pk_bf16_f32 v6, v8, v9
	v_cvt_pk_bf16_f32 v3, v4, v5
	v_cndmask_b32_e32 v5, 0, v3, vcc
	v_cndmask_b32_e32 v3, 0, v6, vcc
	v_cndmask_b32_e32 v4, 0, v2, vcc
	v_cndmask_b32_e32 v2, 0, v0, vcc
	v_addc_co_u32_e64 v33, s[0:1], 0, v31, s[0:1]
	s_mov_b64 s[0:1], 0x1800
	s_nop 0
	v_lshl_add_u64 v[18:19], v[30:31], 0, s[0:1]
	s_mov_b64 s[0:1], 0x1040
	v_lshl_add_u64 v[36:37], v[30:31], 0, s[0:1]
	s_mov_b64 s[0:1], 0x1840
	s_waitcnt vmcnt(13)
	v_mov_b32_e32 v6, v108
	v_mov_b32_e32 v7, v109
	v_mov_b32_e32 v8, v110
	v_mov_b32_e32 v9, v111
	v_cvt_pk_bf16_f32 v6, v6, v7
	s_waitcnt vmcnt(12)
	v_mov_b32_e32 v10, v112
	v_mov_b32_e32 v11, v113
	v_mov_b32_e32 v12, v114
	v_mov_b32_e32 v13, v115
	v_cvt_pk_bf16_f32 v0, v10, v11
	v_cvt_pk_bf16_f32 v10, v12, v13
	v_cvt_pk_bf16_f32 v7, v8, v9
	v_cndmask_b32_e32 v9, 0, v7, vcc
	v_cndmask_b32_e32 v7, 0, v10, vcc
	s_nop 0
	v_cndmask_b32_e32 v8, 0, v6, vcc
	v_cndmask_b32_e32 v6, 0, v0, vcc
	s_waitcnt vmcnt(11)
	v_mov_b32_e32 v10, v116
	v_mov_b32_e32 v11, v117
	v_mov_b32_e32 v12, v118
	v_mov_b32_e32 v13, v119
	v_cvt_pk_bf16_f32 v0, v10, v11
	v_cvt_pk_bf16_f32 v10, v12, v13
	s_waitcnt vmcnt(10)
	v_mov_b32_e32 v14, v120
	v_mov_b32_e32 v15, v121
	v_mov_b32_e32 v16, v122
	v_mov_b32_e32 v17, v123
	v_cvt_pk_bf16_f32 v12, v14, v15
	v_cvt_pk_bf16_f32 v13, v16, v17
	s_nop 0
	v_cndmask_b32_e32 v11, 0, v10, vcc
	v_cndmask_b32_e32 v10, 0, v0, vcc
	v_cndmask_b32_e32 v13, 0, v13, vcc
	v_cndmask_b32_e32 v12, 0, v12, vcc
	s_waitcnt vmcnt(9)
	v_mov_b32_e32 v14, v124
	v_mov_b32_e32 v15, v125
	v_mov_b32_e32 v16, v126
	v_mov_b32_e32 v17, v127
	v_cvt_pk_bf16_f32 v0, v14, v15
	v_cvt_pk_bf16_f32 v14, v16, v17
	s_waitcnt vmcnt(8)
	v_mov_b32_e32 v18, v128
	v_mov_b32_e32 v19, v129
	v_mov_b32_e32 v20, v130
	v_mov_b32_e32 v21, v131
	v_cvt_pk_bf16_f32 v16, v18, v19
	v_cvt_pk_bf16_f32 v17, v20, v21
	v_cndmask_b32_e32 v15, 0, v14, vcc
	v_cndmask_b32_e32 v14, 0, v0, vcc
	v_cndmask_b32_e32 v17, 0, v17, vcc
	v_cndmask_b32_e32 v16, 0, v16, vcc
	s_waitcnt vmcnt(7)
	v_mov_b32_e32 v18, v160
	v_mov_b32_e32 v19, v161
	v_mov_b32_e32 v20, v162
	v_mov_b32_e32 v21, v163
	v_cvt_pk_bf16_f32 v18, v18, v19
	s_waitcnt vmcnt(6)
	v_mov_b32_e32 v22, v164
	v_mov_b32_e32 v23, v165
	v_mov_b32_e32 v24, v166
	v_mov_b32_e32 v25, v167
	v_cvt_pk_bf16_f32 v0, v22, v23
	v_cvt_pk_bf16_f32 v22, v24, v25
	v_cvt_pk_bf16_f32 v19, v20, v21
	v_cndmask_b32_e32 v21, 0, v19, vcc
	v_cndmask_b32_e32 v19, 0, v22, vcc
	v_cndmask_b32_e32 v20, 0, v18, vcc
	v_cndmask_b32_e32 v18, 0, v0, vcc
	s_waitcnt vmcnt(5)
	v_mov_b32_e32 v22, v168
	v_mov_b32_e32 v23, v169
	v_mov_b32_e32 v24, v170
	v_mov_b32_e32 v25, v171
	v_cvt_pk_bf16_f32 v22, v22, v23
	s_waitcnt vmcnt(4)
	v_mov_b32_e32 v26, v172
	v_mov_b32_e32 v27, v173
	v_mov_b32_e32 v28, v174
	v_mov_b32_e32 v29, v175
	v_cvt_pk_bf16_f32 v0, v26, v27
	v_cvt_pk_bf16_f32 v26, v28, v29
	v_cvt_pk_bf16_f32 v23, v24, v25
	v_cndmask_b32_e32 v25, 0, v23, vcc
	v_cndmask_b32_e32 v23, 0, v26, vcc
	s_nop 0
	v_cndmask_b32_e32 v24, 0, v22, vcc
	v_cndmask_b32_e32 v22, 0, v0, vcc
	s_waitcnt vmcnt(3)
	v_mov_b32_e32 v26, v176
	v_mov_b32_e32 v27, v177
	v_mov_b32_e32 v28, v178
	v_mov_b32_e32 v29, v179
	v_cvt_pk_bf16_f32 v0, v26, v27
	v_cvt_pk_bf16_f32 v26, v28, v29
	s_waitcnt vmcnt(2)
; #define TIDX tid_()
; DEVI unsigned pk_bf16(float lo, float hi) { const bf16x2n r = __builtin_convertvector((f32x2v){lo, hi}, bf16x2n); return __builtin_bit_cast(unsigned, r); }
; DEVI bf16_t f2bf(float f) { return (bf16_t)(pk_bf16(f, 0.f) & 0xffffu); }
; DEVI f32x4 mfma16(bf16x8 a, bf16x8 b, f32x4 c) { return __builtin_amdgcn_mfma_f32_16x16x32_bf16(a, b, c, 0, 0, 0); }
; DEVI void s5_load_u(const float* ussm, int tok0, int G, float* us, int lane) {
;     const float* up = ussm + (size_t)(tok0 + lane) * 256 + G * 16;
; #pragma unroll
;     for (int i = 0; i < 4; ++i) *(f32x4*)(us + lane * 16 + i * 4) = *(const f32x4*)(up + i * 4);
; }
; DEVI void s5_x_half(const float* us, bf16_t* XH, const bf16x8 (&bf)[8], int half) {
;     const int lane = TIDX & 63, l16 = lane & 15, quad = lane >> 4;
; #pragma unroll
;     for (int mt = 0; mt < 2; ++mt) {
;         const float* up = us + (half * 32 + mt * 16 + l16) * 16 + (quad & 1) * 8;
;         const f32x4 a = *(const f32x4*)up, c = *(const f32x4*)(up + 4);
;         u32x4 v = (u32x4){pk_bf16(a[0], a[1]), pk_bf16(a[2], a[3]), pk_bf16(c[0], c[1]), pk_bf16(c[2], c[3])};
;         if (quad >= 2) v = (u32x4){0u, 0u, 0u, 0u};
;         const bf16x8 af = __builtin_bit_cast(bf16x8, v);
; #pragma unroll
;         for (int nt = 0; nt < 8; ++nt) {
;             const f32x4 acc = mfma16(af, bf[nt], (f32x4){0.f, 0.f, 0.f, 0.f});
; #pragma unroll
;             for (int r = 0; r < 4; ++r) XH[(mt * 16 + quad * 4 + r) * 136 + nt * 16 + l16] = f2bf(acc[r]);
;         }
;     }
; }
	v_mov_b32_e32 v36, v180
	v_mov_b32_e32 v37, v181
	v_mov_b32_e32 v38, v182
	v_mov_b32_e32 v39, v183
	v_cvt_pk_bf16_f32 v28, v36, v37
	v_lshl_add_u64 v[36:37], v[30:31], 0, s[0:1]
	v_cvt_pk_bf16_f32 v29, v38, v39
	s_nop 0
	s_lshl_b32 s0, s31, 13
	s_lshl_b32 s1, s30, 6
	s_or_b32 s0, s1, s0
	v_cndmask_b32_e32 v27, 0, v26, vcc
	v_cndmask_b32_e32 v26, 0, v0, vcc
	v_cndmask_b32_e32 v29, 0, v29, vcc
	v_cndmask_b32_e32 v28, 0, v28, vcc
	s_waitcnt vmcnt(1)
	v_mov_b32_e32 v30, v184
	v_mov_b32_e32 v31, v185
	v_mov_b32_e32 v32, v186
	v_mov_b32_e32 v33, v187
	v_cvt_pk_bf16_f32 v0, v30, v31
	v_cvt_pk_bf16_f32 v30, v32, v33
	s_waitcnt vmcnt(0)
	v_mov_b32_e32 v36, v188
	v_mov_b32_e32 v37, v189
	v_mov_b32_e32 v38, v190
	v_mov_b32_e32 v39, v191
	v_cvt_pk_bf16_f32 v32, v36, v37
	v_or_b32_e32 v36, s0, v40
	v_ashrrev_i32_e32 v37, 31, v36
	v_lshlrev_b64 v[36:37], 10, v[36:37]
	v_lshl_add_u64 v[36:37], s[24:25], 0, v[36:37]
	v_lshl_add_u64 v[50:51], v[36:37], 0, s[22:23]
	v_cvt_pk_bf16_f32 v33, v38, v39
	global_load_dwordx4 v[36:39], v[50:51], off offset:48
	global_load_dwordx4 v[42:45], v[50:51], off offset:32
	global_load_dwordx4 v[46:49], v[50:51], off offset:16
	s_nop 0
	global_load_dwordx4 v[50:53], v[50:51], off
	v_cndmask_b32_e32 v31, 0, v30, vcc
	v_cndmask_b32_e32 v30, 0, v0, vcc
	v_lshl_or_b32 v0, v40, 6, s38
	s_movk_i32 s0, 0xffc2
	v_mad_i32_i24 v41, v40, s0, v0
	v_cndmask_b32_e32 v33, 0, v33, vcc
	v_cndmask_b32_e32 v32, 0, v32, vcc
	s_waitcnt vmcnt(0)
	ds_write_b128 v0, v[50:53]
	ds_write_b128 v0, v[46:49] offset:16
	ds_write_b128 v0, v[42:45] offset:32
	ds_write_b128 v0, v[36:39] offset:48
	v_mov_b32_e32 v0, v133
	s_nop 0
	v_and_b32_e32 v46, 15, v0
	v_bfe_u32 v47, v0, 4, 2
	v_lshlrev_b32_e32 v0, 1, v0
	v_and_b32_e32 v0, 32, v0
	v_lshlrev_b32_e32 v36, 6, v46
	v_or3_b32 v0, s38, v0, v36
	ds_read_b128 v[36:39], v0
	ds_read_b128 v[42:45], v0 offset:16
	v_cmp_lt_u32_e32 vcc, 1, v47
	v_mul_u32_u24_e32 v47, 0x440, v47
	v_lshlrev_b32_e32 v46, 1, v46
	s_waitcnt lgkmcnt(1)
	v_cvt_pk_bf16_f32 v36, v36, v37
	v_cvt_pk_bf16_f32 v37, v38, v39
	s_waitcnt lgkmcnt(0)
	v_cvt_pk_bf16_f32 v38, v42, v43
	v_cvt_pk_bf16_f32 v39, v44, v45
	v_cndmask_b32_e64 v39, v39, 0, vcc
	v_cndmask_b32_e64 v38, v38, 0, vcc
	v_cndmask_b32_e64 v37, v37, 0, vcc
	v_cndmask_b32_e64 v36, v36, 0, vcc
	v_or3_b32 v46, s38, v47, v46
	s_nop 0
	v_mfma_f32_16x16x32_bf16 v[42:45], v[36:39], v[2:5], 0
	s_nop 7
	v_cvt_pk_bf16_f32 v42, v42, s0
	ds_write_b16 v46, v42 offset:4096
	v_cvt_pk_bf16_f32 v42, v43, s0
	ds_write_b16 v46, v42 offset:4368
	v_cvt_pk_bf16_f32 v42, v44, s0
	ds_write_b16 v46, v42 offset:4640
	v_cvt_pk_bf16_f32 v42, v45, s0
	ds_write_b16 v46, v42 offset:4912
	v_mfma_f32_16x16x32_bf16 v[42:45], v[36:39], v[6:9], 0
	s_nop 7
	v_cvt_pk_bf16_f32 v42, v42, s0
	ds_write_b16 v46, v42 offset:4128
	v_cvt_pk_bf16_f32 v42, v43, s0
	ds_write_b16 v46, v42 offset:4400
	v_cvt_pk_bf16_f32 v42, v44, s0
	ds_write_b16 v46, v42 offset:4672
	v_cvt_pk_bf16_f32 v42, v45, s0
	ds_write_b16 v46, v42 offset:4944
	v_mfma_f32_16x16x32_bf16 v[42:45], v[36:39], v[10:13], 0
	s_nop 7
	v_cvt_pk_bf16_f32 v42, v42, s0
	ds_write_b16 v46, v42 offset:4160
	v_cvt_pk_bf16_f32 v42, v43, s0
	ds_write_b16 v46, v42 offset:4432
	v_cvt_pk_bf16_f32 v42, v44, s0
	ds_write_b16 v46, v42 offset:4704
	v_cvt_pk_bf16_f32 v42, v45, s0
	ds_write_b16 v46, v42 offset:4976
	v_mfma_f32_16x16x32_bf16 v[42:45], v[36:39], v[14:17], 0
	s_nop 7
	v_cvt_pk_bf16_f32 v42, v42, s0
	ds_write_b16 v46, v42 offset:4192
	v_cvt_pk_bf16_f32 v42, v43, s0
	ds_write_b16 v46, v42 offset:4464
	v_cvt_pk_bf16_f32 v42, v44, s0
	ds_write_b16 v46, v42 offset:4736
	v_cvt_pk_bf16_f32 v42, v45, s0
	ds_write_b16 v46, v42 offset:5008
	v_mfma_f32_16x16x32_bf16 v[42:45], v[36:39], v[18:21], 0
	s_nop 7
	v_cvt_pk_bf16_f32 v42, v42, s0
	ds_write_b16 v46, v42 offset:4224
	v_cvt_pk_bf16_f32 v42, v43, s0
	ds_write_b16 v46, v42 offset:4496
	v_cvt_pk_bf16_f32 v42, v44, s0
	ds_write_b16 v46, v42 offset:4768
	v_cvt_pk_bf16_f32 v42, v45, s0
	ds_write_b16 v46, v42 offset:5040
	v_mfma_f32_16x16x32_bf16 v[42:45], v[36:39], v[22:25], 0
	s_nop 7
	v_cvt_pk_bf16_f32 v42, v42, s0
	ds_write_b16 v46, v42 offset:4256
	v_cvt_pk_bf16_f32 v42, v43, s0
	ds_write_b16 v46, v42 offset:4528
	v_cvt_pk_bf16_f32 v42, v44, s0
	ds_write_b16 v46, v42 offset:4800
	v_cvt_pk_bf16_f32 v42, v45, s0
	ds_write_b16 v46, v42 offset:5072
	v_mfma_f32_16x16x32_bf16 v[42:45], v[36:39], v[26:29], 0
	v_mfma_f32_16x16x32_bf16 v[36:39], v[36:39], v[30:33], 0
	s_nop 6
	v_cvt_pk_bf16_f32 v42, v42, s0
	v_cvt_pk_bf16_f32 v36, v36, s0
	ds_write_b16 v46, v42 offset:4288
	v_cvt_pk_bf16_f32 v42, v43, s0
	ds_write_b16 v46, v36 offset:4320
	v_cvt_pk_bf16_f32 v36, v37, s0
	ds_write_b16 v46, v42 offset:4560
	v_cvt_pk_bf16_f32 v42, v44, s0
	ds_write_b16 v46, v36 offset:4592
	v_cvt_pk_bf16_f32 v36, v38, s0
	ds_write_b16 v46, v42 offset:4832
	v_cvt_pk_bf16_f32 v42, v45, s0
	ds_write_b16 v46, v36 offset:4864
	v_cvt_pk_bf16_f32 v36, v39, s0
	ds_write_b16 v46, v42 offset:5104
	ds_write_b16 v46, v36 offset:5136
	ds_read_b128 v[36:39], v0 offset:1024
	ds_read_b128 v[42:45], v0 offset:1040
	s_waitcnt lgkmcnt(1)
; DEVI unsigned pk_bf16(float lo, float hi) { const bf16x2n r = __builtin_convertvector((f32x2v){lo, hi}, bf16x2n); return __builtin_bit_cast(unsigned, r); }
; DEVI bf16_t f2bf(float f) { return (bf16_t)(pk_bf16(f, 0.f) & 0xffffu); }
; DEVI f32x4 mfma16(bf16x8 a, bf16x8 b, f32x4 c) { return __builtin_amdgcn_mfma_f32_16x16x32_bf16(a, b, c, 0, 0, 0); }
; DEVI void s5_x_half(const float* us, bf16_t* XH, const bf16x8 (&bf)[8], int half) {
;     ...
; #pragma unroll
;     for (int mt = 0; mt < 2; ++mt) {
;         const float* up = us + (half * 32 + mt * 16 + l16) * 16 + (quad & 1) * 8;
;         const f32x4 a = *(const f32x4*)up, c = *(const f32x4*)(up + 4);
;         u32x4 v = (u32x4){pk_bf16(a[0], a[1]), pk_bf16(a[2], a[3]), pk_bf16(c[0], c[1]), pk_bf16(c[2], c[3])};
;         if (quad >= 2) v = (u32x4){0u, 0u, 0u, 0u};
;         const bf16x8 af = __builtin_bit_cast(bf16x8, v);
; #pragma unroll
;         for (int nt = 0; nt < 8; ++nt) {
;             const f32x4 acc = mfma16(af, bf[nt], (f32x4){0.f, 0.f, 0.f, 0.f});
; #pragma unroll
;             for (int r = 0; r < 4; ++r) XH[(mt * 16 + quad * 4 + r) * 136 + nt * 16 + l16] = f2bf(acc[r]);
;         }
;     }
; }
	v_cvt_pk_bf16_f32 v0, v36, v37
	v_cvt_pk_bf16_f32 v36, v38, v39
	s_waitcnt lgkmcnt(0)
	v_cvt_pk_bf16_f32 v37, v42, v43
	v_cvt_pk_bf16_f32 v38, v44, v45
	v_cndmask_b32_e64 v39, v38, 0, vcc
	v_cndmask_b32_e64 v38, v37, 0, vcc
	v_cndmask_b32_e64 v37, v36, 0, vcc
	v_cndmask_b32_e64 v36, v0, 0, vcc
	s_nop 1
	v_mfma_f32_16x16x32_bf16 v[42:45], v[36:39], v[2:5], 0
	s_nop 7
	v_cvt_pk_bf16_f32 v0, v42, s0
	ds_write_b16 v46, v0 offset:8448
	v_cvt_pk_bf16_f32 v0, v43, s0
	ds_write_b16 v46, v0 offset:8720
	v_cvt_pk_bf16_f32 v0, v44, s0
	ds_write_b16 v46, v0 offset:8992
	v_cvt_pk_bf16_f32 v0, v45, s0
	v_mfma_f32_16x16x32_bf16 v[42:45], v[36:39], v[6:9], 0
	ds_write_b16 v46, v0 offset:9264
	s_nop 6
	v_cvt_pk_bf16_f32 v0, v42, s0
	ds_write_b16 v46, v0 offset:8480
	v_cvt_pk_bf16_f32 v0, v43, s0
	ds_write_b16 v46, v0 offset:8752
	v_cvt_pk_bf16_f32 v0, v44, s0
	ds_write_b16 v46, v0 offset:9024
	v_cvt_pk_bf16_f32 v0, v45, s0
	v_mfma_f32_16x16x32_bf16 v[42:45], v[36:39], v[10:13], 0
	ds_write_b16 v46, v0 offset:9296
	s_nop 6
	v_cvt_pk_bf16_f32 v0, v42, s0
	ds_write_b16 v46, v0 offset:8512
	v_cvt_pk_bf16_f32 v0, v43, s0
	ds_write_b16 v46, v0 offset:8784
	v_cvt_pk_bf16_f32 v0, v44, s0
	ds_write_b16 v46, v0 offset:9056
	v_cvt_pk_bf16_f32 v0, v45, s0
	v_mfma_f32_16x16x32_bf16 v[42:45], v[36:39], v[14:17], 0
	ds_write_b16 v46, v0 offset:9328
	s_nop 6
	v_cvt_pk_bf16_f32 v0, v42, s0
	ds_write_b16 v46, v0 offset:8544
	v_cvt_pk_bf16_f32 v0, v43, s0
	ds_write_b16 v46, v0 offset:8816
	v_cvt_pk_bf16_f32 v0, v44, s0
	ds_write_b16 v46, v0 offset:9088
	v_cvt_pk_bf16_f32 v0, v45, s0
	v_mfma_f32_16x16x32_bf16 v[42:45], v[36:39], v[18:21], 0
	ds_write_b16 v46, v0 offset:9360
	s_nop 6
	v_cvt_pk_bf16_f32 v0, v42, s0
	ds_write_b16 v46, v0 offset:8576
	v_cvt_pk_bf16_f32 v0, v43, s0
	ds_write_b16 v46, v0 offset:8848
	v_cvt_pk_bf16_f32 v0, v44, s0
	ds_write_b16 v46, v0 offset:9120
	v_cvt_pk_bf16_f32 v0, v45, s0
	v_mfma_f32_16x16x32_bf16 v[42:45], v[36:39], v[22:25], 0
	ds_write_b16 v46, v0 offset:9392
	s_nop 6
	v_cvt_pk_bf16_f32 v0, v42, s0
	ds_write_b16 v46, v0 offset:8608
	v_cvt_pk_bf16_f32 v0, v43, s0
	ds_write_b16 v46, v0 offset:8880
	v_cvt_pk_bf16_f32 v0, v44, s0
	ds_write_b16 v46, v0 offset:9152
	v_cvt_pk_bf16_f32 v0, v45, s0
	v_mfma_f32_16x16x32_bf16 v[42:45], v[36:39], v[26:29], 0
	ds_write_b16 v46, v0 offset:9424
	v_mfma_f32_16x16x32_bf16 v[36:39], v[36:39], v[30:33], 0
	s_nop 5
	v_cvt_pk_bf16_f32 v0, v42, s0
	ds_write_b16 v46, v0 offset:8640
	v_cvt_pk_bf16_f32 v0, v43, s0
	ds_write_b16 v46, v0 offset:8912
	v_cvt_pk_bf16_f32 v0, v44, s0
	ds_write_b16 v46, v0 offset:9184
	v_cvt_pk_bf16_f32 v0, v45, s0
	ds_write_b16 v46, v0 offset:9456
	v_cvt_pk_bf16_f32 v0, v36, s0
	ds_write_b16 v46, v0 offset:8672
	v_cvt_pk_bf16_f32 v0, v37, s0
	ds_write_b16 v46, v0 offset:8944
	v_cvt_pk_bf16_f32 v0, v38, s0
	ds_write_b16 v46, v0 offset:9216
	v_cvt_pk_bf16_f32 v0, v39, s0
	ds_write_b16 v46, v0 offset:9488
	v_pk_mov_b32 v[36:37], v[34:35], v[34:35] op_sel:[1,0]
	v_mov_b32_e32 v38, 0
	v_mov_b32_e32 v0, 0

; DEVI bf16_t f2bf(float f) { return (bf16_t)(pk_bf16(f, 0.f) & 0xffffu); }
; DEVI void pool_item(const Params& p, int l, int tp, int gi, float* sm) {
;     ...
;     for (int i = 0; i < 5; ++i) {
;         const int idx = i * 256 + tid, row = idx >> 4, c4 = (idx & 15) * 4;
;         const int sidx = s0 - 16 + row;
;         const f32x4 v = sidx >= 0 ? *(const f32x4*)(upool + (size_t)(tok0 - 16 + row) * 256 + gi * 64 + c4) : (f32x4){0.f, 0.f, 0.f, 0.f};
;         *(f32x4*)(ul + row * 64 + c4) = v;
;     }
;     {
;         const float* wp = p.pool_w + ((size_t)(l * 4 + gi) * 64) * 64;
; #pragma unroll
;         for (int i = 0; i < 4; ++i) {
;             const int idx = i * 256 + tid, c = idx >> 4, d4 = (idx & 15) * 4;
;             const f32x4 v = *(const f32x4*)(wp + c * 64 + d4);
; #pragma unroll
;             for (int e = 0; e < 4; ++e) wt[(d4 + e) * 72 + c] = f2bf(v[e]);
;         }
;     }
.LBB0_52:
	s_and_b64 vcc, exec, s[0:1]
	s_cbranch_vccz .LBB0_76
	s_lshl_b32 s0, s64, 4
	s_and_b32 s31, s0, 0x7fc0
	v_mov_b32_e32 v10, v133
	v_mov_b32_e32 v0, v133
	s_add_i32 s22, s31, 0xfffff800
	s_and_b32 s39, s64, 3
	s_and_b32 s38, s22, 0x1fc0
	v_readfirstlane_b32 s30, v0
	v_lshlrev_b32_e32 v0, 2, v10
	s_sub_i32 s65, 15, s38
	s_addk_i32 s31, 0xf7f0
	s_lshl_b32 s0, s39, 8
	v_and_b32_e32 v11, 60, v0
	s_add_u32 s0, s40, s0
	s_addc_u32 s1, s41, 0
	v_lshlrev_b32_e32 v0, 2, v11
	v_ashrrev_i32_e32 v14, 4, v10
	v_lshl_add_u64 v[8:9], s[0:1], 0, v[0:1]
	v_mov_b32_e32 v96, v14
	v_cmp_lt_i32_e32 vcc, s65, v96
	v_mov_b32_e32 v100, 0
	v_mov_b32_e32 v101, 0
	v_mov_b32_e32 v102, 0
	v_mov_b32_e32 v103, 0
	s_and_saveexec_b64 s[80:81], vcc
	v_add_u32_e32 v96, s31, v96
	v_ashrrev_i32_e32 v97, 31, v96
	v_lshlrev_b64 v[96:97], 10, v[96:97]
	v_lshl_add_u64 v[96:97], v[8:9], 0, v[96:97]
	global_load_dwordx4 v[100:103], v[96:97], off
	s_or_b64 exec, exec, s[80:81]
	v_add_u32_e32 v96, 16, v14
	v_cmp_lt_i32_e32 vcc, s65, v96
	v_mov_b32_e32 v104, 0
	v_mov_b32_e32 v105, 0
	v_mov_b32_e32 v106, 0
	v_mov_b32_e32 v107, 0
	s_and_saveexec_b64 s[80:81], vcc
	v_add_u32_e32 v96, s31, v96
	v_ashrrev_i32_e32 v97, 31, v96
	v_lshlrev_b64 v[96:97], 10, v[96:97]
	v_lshl_add_u64 v[96:97], v[8:9], 0, v[96:97]
	global_load_dwordx4 v[104:107], v[96:97], off
	s_or_b64 exec, exec, s[80:81]
	v_add_u32_e32 v96, 32, v14
	v_cmp_lt_i32_e32 vcc, s65, v96
	v_mov_b32_e32 v108, 0
	v_mov_b32_e32 v109, 0
	v_mov_b32_e32 v110, 0
	v_mov_b32_e32 v111, 0
	s_and_saveexec_b64 s[80:81], vcc
	v_add_u32_e32 v96, s31, v96
	v_ashrrev_i32_e32 v97, 31, v96
	v_lshlrev_b64 v[96:97], 10, v[96:97]
	v_lshl_add_u64 v[96:97], v[8:9], 0, v[96:97]
	global_load_dwordx4 v[108:111], v[96:97], off
	s_or_b64 exec, exec, s[80:81]
	v_add_u32_e32 v96, 48, v14
	v_cmp_lt_i32_e32 vcc, s65, v96
	v_mov_b32_e32 v112, 0
	v_mov_b32_e32 v113, 0
	v_mov_b32_e32 v114, 0
	v_mov_b32_e32 v115, 0
	s_and_saveexec_b64 s[80:81], vcc
	v_add_u32_e32 v96, s31, v96
	v_ashrrev_i32_e32 v97, 31, v96
	v_lshlrev_b64 v[96:97], 10, v[96:97]
	v_lshl_add_u64 v[96:97], v[8:9], 0, v[96:97]
	global_load_dwordx4 v[112:115], v[96:97], off
	s_or_b64 exec, exec, s[80:81]
	v_add_u32_e32 v96, 64, v14
	v_cmp_lt_i32_e32 vcc, s65, v96
	v_mov_b32_e32 v116, 0
	v_mov_b32_e32 v117, 0
	v_mov_b32_e32 v118, 0
	v_mov_b32_e32 v119, 0
	s_and_saveexec_b64 s[80:81], vcc
	v_add_u32_e32 v96, s31, v96
	v_ashrrev_i32_e32 v97, 31, v96
	v_lshlrev_b64 v[96:97], 10, v[96:97]
	v_lshl_add_u64 v[96:97], v[8:9], 0, v[96:97]
	global_load_dwordx4 v[116:119], v[96:97], off
	s_or_b64 exec, exec, s[80:81]
	s_or_b32 s80, s39, s10
	s_ashr_i32 s81, s80, 31
	s_lshl_b64 s[80:81], s[80:81], 14
	v_readlane_b32 s82, v223, 12
	v_readlane_b32 s83, v223, 13
	s_add_u32 s80, s82, s80
	s_addc_u32 s81, s83, s81
	v_lshl_add_u64 v[98:99], s[80:81], 0, v[0:1]
	v_mov_b32_e32 v96, v14
	v_lshlrev_b32_e32 v96, 8, v96
	v_mov_b32_e32 v97, 0
	v_lshl_add_u64 v[96:97], v[98:99], 0, v[96:97]
	global_load_dwordx4 v[120:123], v[96:97], off
	v_add_u32_e32 v96, 16, v14
	v_lshlrev_b32_e32 v96, 8, v96
	v_mov_b32_e32 v97, 0
	v_lshl_add_u64 v[96:97], v[98:99], 0, v[96:97]
	global_load_dwordx4 v[124:127], v[96:97], off
	v_add_u32_e32 v96, 32, v14
	v_lshlrev_b32_e32 v96, 8, v96
	v_mov_b32_e32 v97, 0
	v_lshl_add_u64 v[96:97], v[98:99], 0, v[96:97]
	global_load_dwordx4 v[128:131], v[96:97], off
	v_add_u32_e32 v96, 48, v14
	v_lshlrev_b32_e32 v96, 8, v96
	v_mov_b32_e32 v97, 0
	v_lshl_add_u64 v[96:97], v[98:99], 0, v[96:97]
	global_load_dwordx4 v[160:163], v[96:97], off
	v_cmp_lt_i32_e32 vcc, s65, v14
	v_mov_b32_e32 v2, 0
	v_mov_b32_e32 v4, 0
	v_mov_b32_e32 v5, 0
	v_mov_b32_e32 v6, 0
	v_mov_b32_e32 v7, 0
	s_and_saveexec_b64 s[0:1], vcc
	s_cbranch_execz .LBB0_55
	v_add_u32_e32 v4, s31, v14
	v_ashrrev_i32_e32 v5, 31, v4
	v_lshlrev_b64 v[4:5], 10, v[4:5]
	v_lshl_add_u64 v[4:5], v[8:9], 0, v[4:5]
.LBB0_55:
	s_or_b64 exec, exec, s[0:1]
	v_lshl_or_b32 v3, v14, 8, v0
	s_waitcnt vmcnt(8)
	v_mov_b32_e32 v4, v100
	v_mov_b32_e32 v5, v101
	v_mov_b32_e32 v6, v102
	v_mov_b32_e32 v7, v103
	ds_write_b128 v3, v[4:7]
	v_add_u32_e32 v3, 0x100, v10
	v_ashrrev_i32_e32 v13, 4, v3
	v_cmp_lt_i32_e32 vcc, s65, v13
	v_mov_b32_e32 v3, 0
	v_mov_b32_e32 v4, 0
	v_mov_b32_e32 v5, 0
	s_and_saveexec_b64 s[0:1], vcc
	s_cbranch_execz .LBB0_57
	v_add_u32_e32 v2, s31, v13
	v_ashrrev_i32_e32 v3, 31, v2
	v_lshlrev_b64 v[2:3], 10, v[2:3]
	v_lshl_add_u64 v[2:3], v[8:9], 0, v[2:3]
; DEVI bf16_t f2bf(float f) { return (bf16_t)(pk_bf16(f, 0.f) & 0xffffu); }
; DEVI void pool_item(const Params& p, int l, int tp, int gi, float* sm) {
;     ...
;     for (int i = 0; i < 5; ++i) {
;         const int idx = i * 256 + tid, row = idx >> 4, c4 = (idx & 15) * 4;
;         const int sidx = s0 - 16 + row;
;         const f32x4 v = sidx >= 0 ? *(const f32x4*)(upool + (size_t)(tok0 - 16 + row) * 256 + gi * 64 + c4) : (f32x4){0.f, 0.f, 0.f, 0.f};
;         *(f32x4*)(ul + row * 64 + c4) = v;
;     }
;     {
;         const float* wp = p.pool_w + ((size_t)(l * 4 + gi) * 64) * 64;
; #pragma unroll
;         for (int i = 0; i < 4; ++i) {
;             const int idx = i * 256 + tid, c = idx >> 4, d4 = (idx & 15) * 4;
;             const f32x4 v = *(const f32x4*)(wp + c * 64 + d4);
; #pragma unroll
;             for (int e = 0; e < 4; ++e) wt[(d4 + e) * 72 + c] = f2bf(v[e]);
;         }
;     }
;     __syncthreads();
.LBB0_57:
	s_or_b64 exec, exec, s[0:1]
	v_lshl_or_b32 v6, v13, 8, v0
	s_waitcnt vmcnt(7)
	v_mov_b32_e32 v2, v104
	v_mov_b32_e32 v3, v105
	v_mov_b32_e32 v4, v106
	v_mov_b32_e32 v5, v107
	ds_write_b128 v6, v[2:5]
	v_add_u32_e32 v2, 0x200, v10
	v_ashrrev_i32_e32 v12, 4, v2
	v_cmp_lt_i32_e32 vcc, s65, v12
	v_mov_b32_e32 v2, 0
	v_mov_b32_e32 v4, 0
	v_mov_b32_e32 v5, 0
	v_mov_b32_e32 v6, 0
	v_mov_b32_e32 v7, 0
	s_and_saveexec_b64 s[0:1], vcc
	s_cbranch_execz .LBB0_59
	v_add_u32_e32 v4, s31, v12
	v_ashrrev_i32_e32 v5, 31, v4
	v_lshlrev_b64 v[4:5], 10, v[4:5]
	v_lshl_add_u64 v[4:5], v[8:9], 0, v[4:5]
.LBB0_59:
	s_or_b64 exec, exec, s[0:1]
	v_lshl_or_b32 v3, v12, 8, v0
	s_waitcnt vmcnt(6)
	v_mov_b32_e32 v4, v108
	v_mov_b32_e32 v5, v109
	v_mov_b32_e32 v6, v110
	v_mov_b32_e32 v7, v111
	ds_write_b128 v3, v[4:7]
	v_add_u32_e32 v3, 0x300, v10
	v_ashrrev_i32_e32 v7, 4, v3
	v_cmp_lt_i32_e32 vcc, s65, v7
	v_mov_b32_e32 v3, 0
	v_mov_b32_e32 v4, 0
	v_mov_b32_e32 v5, 0
	s_and_saveexec_b64 s[0:1], vcc
	s_cbranch_execz .LBB0_61
	v_add_u32_e32 v2, s31, v7
	v_ashrrev_i32_e32 v3, 31, v2
	v_lshlrev_b64 v[2:3], 10, v[2:3]
	v_lshl_add_u64 v[2:3], v[8:9], 0, v[2:3]
.LBB0_61:
	s_or_b64 exec, exec, s[0:1]
	v_lshl_or_b32 v6, v7, 8, v0
	s_waitcnt vmcnt(5)
	v_mov_b32_e32 v2, v112
	v_mov_b32_e32 v3, v113
	v_mov_b32_e32 v4, v114
	v_mov_b32_e32 v5, v115
	ds_write_b128 v6, v[2:5]
	v_add_u32_e32 v2, 0x400, v10
	v_ashrrev_i32_e32 v15, 4, v2
	v_cmp_lt_i32_e32 vcc, s65, v15
	v_mov_b32_e32 v6, 0
	v_mov_b32_e32 v2, 0
	v_mov_b32_e32 v3, 0
	v_mov_b32_e32 v4, 0
	v_mov_b32_e32 v5, 0
	s_and_saveexec_b64 s[0:1], vcc
	s_cbranch_execz .LBB0_63
	v_add_u32_e32 v2, s31, v15
	v_ashrrev_i32_e32 v3, 31, v2
	v_lshlrev_b64 v[2:3], 10, v[2:3]
	v_lshl_add_u64 v[2:3], v[8:9], 0, v[2:3]
.LBB0_63:
	s_or_b64 exec, exec, s[0:1]
	s_or_b32 s0, s39, s10
	s_ashr_i32 s1, s0, 31
	v_readlane_b32 s80, v223, 10
	s_lshl_b32 s31, s39, 6
	s_lshl_b64 s[0:1], s[0:1], 14
	v_readlane_b32 s82, v223, 12
	v_lshl_or_b32 v8, v15, 8, v0
	v_readlane_b32 s83, v223, 13
	s_add_u32 s0, s82, s0
	s_waitcnt vmcnt(4)
	v_mov_b32_e32 v2, v116
	v_mov_b32_e32 v3, v117
	v_mov_b32_e32 v4, v118
	v_mov_b32_e32 v5, v119
	ds_write_b128 v8, v[2:5]
	s_addc_u32 s1, s83, s1
	v_lshlrev_b32_e32 v8, 6, v14
	v_lshl_add_u64 v[4:5], s[0:1], 0, v[0:1]
	v_ashrrev_i32_e32 v9, 31, v8
	v_lshl_add_u64 v[8:9], v[8:9], 2, v[4:5]
	v_mul_u32_u24_e32 v3, 0x90, v11
	v_lshl_add_u32 v8, v14, 1, v3
	v_and_b32_e32 v2, 63, v10
	v_readlane_b32 s81, v223, 11
	v_readlane_b32 s84, v223, 14
	v_readlane_b32 s85, v223, 15
	v_readlane_b32 s86, v223, 16
	v_readlane_b32 s87, v223, 17
	v_readlane_b32 s88, v223, 18
	v_readlane_b32 s89, v223, 19
	v_readlane_b32 s90, v223, 20
	v_readlane_b32 s91, v223, 21
	v_readlane_b32 s92, v223, 22
	v_readlane_b32 s93, v223, 23
	v_readlane_b32 s94, v223, 24
	v_readlane_b32 s95, v223, 25
	s_waitcnt vmcnt(3)
	v_mov_b32_e32 v16, v120
	v_mov_b32_e32 v17, v121
	v_mov_b32_e32 v18, v122
	v_mov_b32_e32 v19, v123
	v_cvt_pk_bf16_f32 v0, v16, s0
	ds_write_b16 v8, v0 offset:29696
	v_cvt_pk_bf16_f32 v0, v17, s0
	ds_write_b16 v8, v0 offset:29840
	v_cvt_pk_bf16_f32 v0, v18, s0
	ds_write_b16 v8, v0 offset:29984
	v_cvt_pk_bf16_f32 v0, v19, s0
	ds_write_b16 v8, v0 offset:30128
	v_lshlrev_b32_e32 v8, 6, v13
	v_ashrrev_i32_e32 v9, 31, v8
	v_lshl_add_u64 v[8:9], v[8:9], 2, v[4:5]
	v_lshl_add_u32 v8, v13, 1, v3
	s_waitcnt vmcnt(2)
	v_mov_b32_e32 v14, v124
	v_mov_b32_e32 v15, v125
	v_mov_b32_e32 v16, v126
	v_mov_b32_e32 v17, v127
	v_cvt_pk_bf16_f32 v0, v14, s0
	ds_write_b16 v8, v0 offset:29696
	v_cvt_pk_bf16_f32 v0, v15, s0
	ds_write_b16 v8, v0 offset:29840
	v_cvt_pk_bf16_f32 v0, v16, s0
	ds_write_b16 v8, v0 offset:29984
	v_cvt_pk_bf16_f32 v0, v17, s0
	ds_write_b16 v8, v0 offset:30128
	v_lshlrev_b32_e32 v8, 6, v12
	v_ashrrev_i32_e32 v9, 31, v8
	v_lshl_add_u64 v[8:9], v[8:9], 2, v[4:5]
	v_lshl_add_u32 v8, v12, 1, v3
	v_lshl_add_u32 v3, v7, 1, v3
	s_waitcnt vmcnt(1)
	v_mov_b32_e32 v14, v128
	v_mov_b32_e32 v15, v129
	v_mov_b32_e32 v16, v130
	v_mov_b32_e32 v17, v131
	v_cvt_pk_bf16_f32 v0, v14, s0
	ds_write_b16 v8, v0 offset:29696
	v_cvt_pk_bf16_f32 v0, v15, s0
	ds_write_b16 v8, v0 offset:29840
	v_cvt_pk_bf16_f32 v0, v16, s0
	ds_write_b16 v8, v0 offset:29984
	v_cvt_pk_bf16_f32 v0, v17, s0
	ds_write_b16 v8, v0 offset:30128
	v_lshlrev_b32_e32 v8, 6, v7
	v_ashrrev_i32_e32 v9, 31, v8
	v_lshl_add_u64 v[4:5], v[8:9], 2, v[4:5]
	s_waitcnt vmcnt(0)
	v_mov_b32_e32 v12, v160
	v_mov_b32_e32 v13, v161
	v_mov_b32_e32 v14, v162
	v_mov_b32_e32 v15, v163
	v_cvt_pk_bf16_f32 v0, v12, s0
	ds_write_b16 v3, v0 offset:29696
	v_cvt_pk_bf16_f32 v0, v13, s0
	ds_write_b16 v3, v0 offset:29840
	v_cvt_pk_bf16_f32 v0, v14, s0
	ds_write_b16 v3, v0 offset:29984
	v_cvt_pk_bf16_f32 v0, v15, s0
	ds_write_b16 v3, v0 offset:30128
	v_ashrrev_i32_e32 v3, 2, v10
	v_lshrrev_b32_e32 v4, 4, v3
	v_lshlrev_b32_e32 v0, 2, v2
	v_lshl_or_b32 v0, v4, 12, v0
	s_lshl_b32 s0, 2, s39
	v_add_u32_e32 v0, 0x1000, v0
	s_mov_b32 s1, s0
	v_mov_b32_e32 v5, v0
	s_waitcnt lgkmcnt(0)
	s_barrier
